# scan: U tiles fetched two steps ahead (v224-239), issued mid-step after the record DMA, end-of-step wait vmcnt(4); on top of modpipe
# baseline (speedup 1.0000x reference)
; __device__ __forceinline__ void gdn_scan_phase(const Frame& F0, const Args& a0, int nblk, bool last) {
;     const Frame F = relaunder(F0); const Args a = relaunder_args(a0);
;     const int chain = F.bx; if (chain >= nblk) return;
.LBB0_564:
	s_cmp_eq_u32 s24, 3
	s_cselect_b64 s[76:77], -1, 0
	s_cmp_lg_u32 s24, 3
	s_cselect_b64 s[80:81], -1, 0
	s_cmp_le_i32 s64, s18
	s_cselect_b64 s[2:3], -1, 0
	s_and_b64 s[34:35], s[2:3], s[0:1]
	s_andn2_b64 vcc, exec, s[34:35]
	s_cbranch_vccnz .LBB0_687
	s_mov_b32 s0, s93
	s_mov_b32 s7, s94
	s_mov_b32 s6, s95
	s_mov_b32 s1, s92
	v_readlane_b32 s48, v221, 0
	s_waitcnt vmcnt(0)
	v_mbcnt_lo_u32_b32 v0, -1, 0
	v_mbcnt_hi_u32_b32 v0, -1, v0
	v_readlane_b32 s49, v221, 1
	s_mov_b64 s[0:1], s[48:49]
	v_readlane_b32 s50, v221, 2
	v_readlane_b32 s51, v221, 3
	s_mov_b64 s[0:1], s[50:51]
	v_readlane_b32 s52, v221, 4
	v_readlane_b32 s53, v221, 5
	s_mov_b64 s[0:1], s[52:53]
	v_readlane_b32 s54, v221, 6
	v_readlane_b32 s55, v221, 7
	s_mov_b64 s[0:1], s[54:55]
	v_readlane_b32 s56, v221, 8
	v_readlane_b32 s57, v221, 9
	s_mov_b64 s[0:1], s[56:57]
	v_readlane_b32 s58, v221, 10
	v_readlane_b32 s59, v221, 11
	s_mov_b64 s[0:1], s[58:59]
	v_readlane_b32 s60, v221, 12
	v_readlane_b32 s61, v221, 13
	s_mov_b64 s[0:1], s[60:61]
	v_readlane_b32 s62, v221, 14
	v_readlane_b32 s63, v221, 15
	s_mov_b64 s[0:1], s[62:63]
	v_readlane_b32 s48, v221, 16
	v_readlane_b32 s49, v221, 17
	s_mov_b64 s[0:1], s[48:49]
	v_readlane_b32 s50, v221, 18
	v_readlane_b32 s51, v221, 19
	s_mov_b64 s[0:1], s[50:51]
	v_readlane_b32 s52, v221, 20
	v_readlane_b32 s53, v221, 21
	s_mov_b64 s[0:1], s[52:53]
	v_readlane_b32 s54, v221, 22
	v_readlane_b32 s55, v221, 23
	s_mov_b64 s[0:1], s[54:55]
	v_readlane_b32 s56, v221, 24
	v_readlane_b32 s57, v221, 25
	s_mov_b64 s[0:1], s[56:57]
	v_readlane_b32 s58, v221, 26
	v_readlane_b32 s59, v221, 27
	s_mov_b64 s[0:1], s[58:59]
	v_readlane_b32 s60, v221, 28
	v_readlane_b32 s61, v221, 29
	s_mov_b64 s[0:1], s[60:61]
	v_readlane_b32 s62, v221, 30
	v_readlane_b32 s63, v221, 31
	s_mov_b64 s[0:1], s[62:63]
	s_mov_b64 s[0:1], s[40:41]
	s_mov_b64 s[0:1], s[42:43]
	s_mov_b64 s[0:1], s[44:45]
	s_mov_b64 s[0:1], s[46:47]
	s_cmp_gt_i32 s7, 63
	s_cbranch_scc1 .LBB0_578
; #define VM_WAIT() asm volatile("s_waitcnt vmcnt(0)" ::: "memory")
; #define GD_GLDS(cidx, buf) do { const unsigned char* src_ = REC + (size_t)(cidx) * GD_REC + lane * 16; \
;         _Pragma("unroll") for (int k_ = 0; k_ < 7; ++k_) __builtin_amdgcn_global_load_lds((const unsigned*)(src_ + (n + 8 * k_) * 1024), (LAS unsigned*)(lds + (buf) * GD_REC + (n + 8 * k_) * 1024), 16, 0, 0); } while (0)
; __device__ __forceinline__ void gdn_scan_phase(const Frame& F0, const Args& a0, int nblk, bool last) {
;     ...
;     f32x4 un[4]; float gln;
;     { const int c0 = GD_CHUNK(0); GD_GLDS(c0, 0);
; #pragma unroll
;       for (int mt = 0; mt < 4; ++mt) un[mt] = *(const f32x4*)(UB + (size_t)c0 * 8192 + ((mt * 8 + n) * 64 + lane) * 4);
;       gln = GLB[c0]; }
;     VM_WAIT(); __syncthreads();
	s_and_b64 s[2:3], s[76:77], exec
	s_cselect_b32 s22, 4, 0
	s_and_b32 s10, s7, 1
	s_bfe_i32 s11, s7, 0x10000
	s_lshr_b32 s18, s7, 4
	s_mul_i32 s5, s7, 0x120000
	s_mul_hi_i32 s4, s7, 0x120000
	s_add_u32 s5, s0, s5
	s_addc_u32 s4, s1, s4
	s_add_u32 s23, s5, 0x46e00000
	s_addc_u32 s24, s4, 0
	s_mul_i32 s8, s10, 0x1200000
	s_add_u32 s8, s0, s8
	s_mul_i32 s3, s7, 0x1f8000
	s_addc_u32 s9, s1, 0
	s_mul_hi_i32 s2, s7, 0x1f8000
	s_add_u32 s3, s0, s3
	s_addc_u32 s12, s1, s2
	s_add_u32 s2, s3, 0.5
	s_mul_i32 s5, s7, 0x90
	s_addc_u32 s3, s12, 0
	s_mul_hi_i32 s4, s7, 0x90
	s_add_u32 s0, s0, s5
	s_addc_u32 s1, s1, s4
	s_add_u32 s0, s0, 0x4b600000
	s_addc_u32 s1, s1, 0
	s_cmp_eq_u32 s10, 0
	s_cselect_b64 s[4:5], -1, 0
	s_cmp_eq_u32 s10, 1
	v_and_b32_e32 v8, 1, v0
	s_cselect_b64 s[12:13], -1, 0
	s_and_b32 s14, s11, 3
	v_ashrrev_i32_e32 v2, 2, v0
	v_lshlrev_b32_e32 v3, 1, v8
	s_mul_i32 s10, s14, 0xe000
	v_and_or_b32 v9, v2, -4, v3
	s_add_u32 s10, s2, s10
	v_lshlrev_b32_e32 v2, 4, v0
	s_addc_u32 s11, s3, 0
	v_ashrrev_i32_e32 v3, 31, v2
	s_lshl_b32 s30, s6, 10
	v_lshl_add_u64 v[4:5], s[10:11], 0, v[2:3]
	s_ashr_i32 s31, s30, 31
	s_add_i32 s25, s30, 0
	s_add_i32 s68, s30, 0x2000
	v_lshl_add_u64 v[6:7], v[4:5], 0, s[30:31]
	s_mov_b32 m0, s25
	s_ashr_i32 s69, s68, 31
	s_add_i32 s70, s30, 0x4000
	global_load_lds_dwordx4 v[6:7], off nt
	v_lshl_add_u64 v[6:7], v[4:5], 0, s[68:69]
	s_add_i32 m0, s25, 0x2000
	s_ashr_i32 s71, s70, 31
	s_add_i32 s74, s30, 0x6000
	global_load_lds_dwordx4 v[6:7], off nt
	v_lshl_add_u64 v[6:7], v[4:5], 0, s[70:71]
	s_add_i32 m0, s25, 0x4000
	s_ashr_i32 s75, s74, 31
	s_add_i32 s78, s30, 0x8000
	global_load_lds_dwordx4 v[6:7], off nt
	v_lshl_add_u64 v[6:7], v[4:5], 0, s[74:75]
	s_add_i32 m0, s25, 0x6000
	s_ashr_i32 s79, s78, 31
	s_add_i32 s82, s30, 0xa000
	global_load_lds_dwordx4 v[6:7], off nt
	v_lshl_add_u64 v[6:7], v[4:5], 0, s[78:79]
	s_add_i32 m0, s25, 0x8000
	s_ashr_i32 s83, s82, 31
	v_lshl_add_u32 v1, s6, 6, v0
	global_load_lds_dwordx4 v[6:7], off nt
	v_lshl_add_u64 v[6:7], v[4:5], 0, s[82:83]
	s_add_i32 m0, s25, 0xa000
	s_add_i32 s88, s30, 0xc000
	global_load_lds_dwordx4 v[6:7], off nt
	s_ashr_i32 s89, s88, 31
	s_add_i32 m0, s25, 0xc000
	s_lshl_b32 s10, s14, 15
	v_lshlrev_b32_e32 v70, 2, v1
	s_add_u32 s10, s23, s10
	v_add_u32_e32 v72, 0x800, v70
	v_lshl_add_u64 v[4:5], v[4:5], 0, s[88:89]
	s_addc_u32 s11, s24, 0
	v_ashrrev_i32_e32 v71, 31, v70
	v_ashrrev_i32_e32 v73, 31, v72
	v_add_u32_e32 v74, 0x1000, v70
	v_add_u32_e32 v76, 0x1800, v70
	global_load_lds_dwordx4 v[4:5], off nt
	v_lshl_add_u64 v[4:5], v[70:71], 2, s[10:11]
	v_lshl_add_u64 v[6:7], v[72:73], 2, s[10:11]
	v_ashrrev_i32_e32 v75, 31, v74
	v_ashrrev_i32_e32 v77, 31, v76
	global_load_dwordx4 v[60:63], v[4:5], off nt
	global_load_dwordx4 v[56:59], v[6:7], off nt
	v_lshl_add_u64 v[4:5], v[74:75], 2, s[10:11]
	v_lshl_add_u64 v[6:7], v[76:77], 2, s[10:11]
	s_lshl_b32 s10, s14, 2
	global_load_dwordx4 v[52:55], v[4:5], off nt
	global_load_dwordx4 v[48:51], v[6:7], off nt
	v_mov_b32_e32 v4, s10
	global_load_dword v80, v4, s[0:1]
	s_cmp_eq_u32 s14, 0
	s_cselect_b32 s98, 1, 2
	s_lshl_b32 s98, s98, 15
	s_add_u32 s98, s23, s98
	s_addc_u32 s99, s24, 0
	v_lshl_add_u64 v[240:241], v[70:71], 2, s[98:99]
	v_lshl_add_u64 v[242:243], v[72:73], 2, s[98:99]
	v_lshl_add_u64 v[244:245], v[74:75], 2, s[98:99]
	v_lshl_add_u64 v[246:247], v[76:77], 2, s[98:99]
	global_load_dwordx4 v[236:239], v[240:241], off nt
	global_load_dwordx4 v[232:235], v[242:243], off nt
	global_load_dwordx4 v[228:231], v[244:245], off nt
	global_load_dwordx4 v[224:227], v[246:247], off nt
	v_lshl_add_u64 v[78:79], s[2:3], 0, v[2:3]
	v_and_b32_e32 v160, 0xf0, v2
	s_movk_i32 s2, 0xc0
	v_bitop3_b32 v67, v1, v160, s2 bitop3:0x6c
	s_add_i32 s2, 0, 0x1c000
	v_add_u32_e32 v102, s2, v67
	s_lshl_b32 s2, s7, 7
	s_and_b32 s2, s2, 0x700
	s_add_u32 s2, s8, s2
	s_addc_u32 s3, s9, 0
	v_add_u32_e32 v101, 0, v2
	v_lshl_add_u64 v[2:3], s[2:3], 0, v[160:161]
	s_mov_b64 s[2:3], 0x4b800000
	v_lshl_add_u64 v[64:65], v[2:3], 0, s[2:3]
	v_bfe_u32 v2, v0, 3, 1
	v_lshlrev_b32_e32 v0, 1, v0
	v_sub_u32_e32 v10, 63, v9
	v_and_b32_e32 v84, 12, v0
	v_add_u32_e32 v0, 0x200, v1
	v_lshl_or_b32 v2, s6, 1, v2
	v_ashrrev_i32_e32 v69, 4, v0
	v_cndmask_b32_e64 v0, v10, v9, s[4:5]
	v_lshlrev_b32_e32 v97, 8, v0
	v_bitop3_b32 v0, v0, v2, 12 bitop3:0x6c
	v_lshlrev_b32_e32 v98, 4, v0
	v_or_b32_e32 v0, 1, v9
	v_ashrrev_i32_e32 v82, 4, v1
	v_sub_u32_e32 v1, 63, v0
	v_cndmask_b32_e64 v0, v1, v0, s[4:5]
	v_lshlrev_b32_e32 v99, 8, v0
	v_bitop3_b32 v0, v0, v2, 12 bitop3:0x6c
	v_lshlrev_b32_e32 v100, 4, v0
	v_add_u32_e32 v0, 16, v9
	v_sub_u32_e32 v1, 47, v9
	v_cndmask_b32_e64 v0, v1, v0, s[4:5]
	v_lshlrev_b32_e32 v93, 8, v0
	v_bitop3_b32 v0, v0, v2, 12 bitop3:0x6c
	v_lshlrev_b32_e32 v94, 4, v0
	v_add_u32_e32 v0, 17, v9
	v_sub_u32_e32 v1, 46, v9
	v_cndmask_b32_e64 v0, v1, v0, s[4:5]
	v_lshlrev_b32_e32 v95, 8, v0
	v_bitop3_b32 v0, v0, v2, 12 bitop3:0x6c
	v_lshlrev_b32_e32 v96, 4, v0
	v_add_u32_e32 v0, 32, v9
	v_sub_u32_e32 v1, 31, v9
	v_cndmask_b32_e64 v0, v1, v0, s[4:5]
	v_lshlrev_b32_e32 v89, 8, v0
	v_bitop3_b32 v0, v0, v2, 12 bitop3:0x6c
	v_lshlrev_b32_e32 v90, 4, v0
	v_add_u32_e32 v0, 33, v9
	v_sub_u32_e32 v1, 30, v9
	v_cndmask_b32_e64 v0, v1, v0, s[4:5]
	v_lshlrev_b32_e32 v91, 8, v0
	v_bitop3_b32 v0, v0, v2, 12 bitop3:0x6c
	v_lshlrev_b32_e32 v92, 4, v0
	v_add_u32_e32 v0, 48, v9
	v_sub_u32_e32 v1, 15, v9
	v_cndmask_b32_e64 v0, v1, v0, s[4:5]
	v_lshlrev_b32_e32 v85, 8, v0
	v_bitop3_b32 v0, v0, v2, 12 bitop3:0x6c
	v_lshlrev_b32_e32 v86, 4, v0
	v_add_u32_e32 v0, 49, v9
	v_sub_u32_e32 v1, 14, v9
	v_cndmask_b32_e64 v0, v1, v0, s[4:5]
	s_waitcnt vmcnt(0)
	v_lshlrev_b32_e32 v87, 8, v0
	v_bitop3_b32 v0, v0, v2, 12 bitop3:0x6c
	v_lshlrev_b32_e32 v88, 4, v0
	v_cmp_eq_u32_e64 s[2:3], 0, v8
	v_mov_b32_e32 v0, 0
	s_mov_b32 s19, 0
	s_mulk_i32 s18, 0x900
	v_lshlrev_b32_e32 v83, 8, v82
	v_lshlrev_b32_e32 v81, 8, v69
	v_cndmask_b32_e64 v68, 0, 2, s[2:3]
	v_cndmask_b32_e64 v66, 1, 3, s[2:3]
	s_mov_b32 s27, -1
	s_mov_b32 s26, 38
	s_mov_b32 s8, 0
	v_mov_b32_e32 v1, v0
	v_mov_b32_e32 v2, v0
	v_mov_b32_e32 v3, v0
	v_mov_b32_e32 v4, v0
	v_mov_b32_e32 v5, v0
	v_mov_b32_e32 v6, v0
	v_mov_b32_e32 v7, v0
	v_mov_b32_e32 v8, v0
	v_mov_b32_e32 v9, v0
	v_mov_b32_e32 v10, v0
	v_mov_b32_e32 v11, v0
	v_mov_b32_e32 v12, v0
	v_mov_b32_e32 v13, v0
	v_mov_b32_e32 v14, v0
	v_mov_b32_e32 v15, v0
	v_mov_b32_e32 v16, v0
	v_mov_b32_e32 v17, v0
	v_mov_b32_e32 v18, v0
	v_mov_b32_e32 v19, v0
	v_mov_b32_e32 v20, v0
	v_mov_b32_e32 v21, v0
	v_mov_b32_e32 v22, v0
	v_mov_b32_e32 v23, v0
	v_mov_b32_e32 v24, v0
	v_mov_b32_e32 v25, v0
	v_mov_b32_e32 v26, v0
	v_mov_b32_e32 v27, v0
	v_mov_b32_e32 v28, v0
	v_mov_b32_e32 v29, v0
	v_mov_b32_e32 v30, v0
	v_mov_b32_e32 v31, v0
	s_waitcnt vmcnt(0) lgkmcnt(0)
	s_barrier
	s_cmp_lt_i32 s27, s22
	s_cbranch_scc1 .LBB0_569
	s_branch .LBB0_568

; #define GD_GLDS(cidx, buf) do { const unsigned char* src_ = REC + (size_t)(cidx) * GD_REC + lane * 16; \
;         _Pragma("unroll") for (int k_ = 0; k_ < 7; ++k_) __builtin_amdgcn_global_load_lds((const unsigned*)(src_ + (n + 8 * k_) * 1024), (LAS unsigned*)(lds + (buf) * GD_REC + (n + 8 * k_) * 1024), 16, 0, 0); } while (0)
; #define GD_STORE_ROWS(cidx, buf) do { _Pragma("unroll") for (int i_ = 0; i_ < 2; ++i_) { const int id_ = F.tid + 512 * i_, row_ = id_ >> 4, ch_ = id_ & 15; \
;         const v4u v_ = *(const LAS v4u*)(ost + (buf) * 16384 + row_ * 256 + ((ch_ ^ (((row_ >> 2) & 3) << 2)) * 16)); \
;         *(v4u*)(GOb + (size_t)(b * TT + 64 * (cidx) + row_) * 1024 + h * 128 + ch_ * 8) = v_; } } while (0)
; #define GD_LOAD8(dst, f0) do { _Pragma("unroll") for (int i_ = 0; i_ < 8; ++i_) dst[i_] = GD_FRAG((f0) + i_); } while (0)
; #define GD_PIN() __builtin_amdgcn_sched_barrier(0)
; __device__ __forceinline__ void gdn_scan_phase(const Frame& F0, const Args& a0, int nblk, bool last) {
;     ...
;         f32x4 V[4]; const float gl = gln;
; #pragma unroll
;         for (int mt = 0; mt < 4; ++mt) V[mt] = un[mt];
;         if (cprev >= 0 && !(last && cprev < 4)) GD_STORE_ROWS(cprev, (s + 1) & 1);
;         if (s + 1 < 36) { const int cn = GD_CHUNK(s + 1);
; #pragma unroll
;             for (int mt = 0; mt < 4; ++mt) un[mt] = *(const f32x4*)(UB + (size_t)cn * 8192 + ((mt * 8 + n) * 64 + lane) * 4);
;             gln = GLB[cn];
;             GD_GLDS(cn, (s + 1) & 1); }
;     ...
; #pragma unroll
;         for (int i = 0; i < 8; ++i) V[i >> 2] = __builtin_amdgcn_mfma_f32_16x16x32_bf16(fA[i], Sf[i & 3], V[i >> 2], 0, 0, 0);
;         GD_PIN(); GD_LOAD8(fC, 16); GD_PIN();
; #pragma unroll
;         for (int i = 0; i < 8; ++i) V[2 + (i >> 2)] = __builtin_amdgcn_mfma_f32_16x16x32_bf16(fB[i], Sf[i & 3], V[2 + (i >> 2)], 0, 0, 0);
;         GD_PIN(); GD_LOAD8(fA, 24); GD_PIN();
.LBB0_572:
	s_cmp_gt_u32 s8, 3
	s_cselect_b32 s7, 39, 3
	s_add_i32 s7, s7, s26
	s_sub_i32 s7, s7, 38
	s_and_b64 s[10:11], s[4:5], exec
	s_cselect_b32 s27, s8, s7
	s_ashr_i32 s7, s6, 31
	s_lshl_b64 s[10:11], s[6:7], 15
	s_add_u32 s10, s23, s10
	s_addc_u32 s11, s24, s11
	s_lshl_b64 s[10:11], s[6:7], 2
	s_add_u32 s10, s0, s10
	s_addc_u32 s11, s1, s11
	v_mad_i64_i32 v[104:105], s[6:7], s6, v193, v[78:79]
	s_bitcmp1_b32 s29, 0
	s_cselect_b32 s6, 0xe000, 0
	s_add_i32 s6, s25, s6
	v_lshl_add_u64 v[106:107], v[104:105], 0, s[30:31]
	s_mov_b32 m0, s6
	v_cvt_pk_bf16_f32 v170, v28, v29
	global_load_lds_dwordx4 v[106:107], off nt
	v_lshl_add_u64 v[106:107], v[104:105], 0, s[68:69]
	s_add_i32 m0, s6, 0x2000
	global_load_dword v103, v161, s[10:11]
	v_cvt_pk_bf16_f32 v171, v30, v31
	global_load_lds_dwordx4 v[106:107], off nt
	v_lshl_add_u64 v[106:107], v[104:105], 0, s[70:71]
	s_add_i32 m0, s6, 0x4000
	v_cvt_pk_bf16_f32 v172, v24, v25
	global_load_lds_dwordx4 v[106:107], off nt
	v_lshl_add_u64 v[106:107], v[104:105], 0, s[74:75]
	s_add_i32 m0, s6, 0x6000
	v_cvt_pk_bf16_f32 v173, v26, v27
	global_load_lds_dwordx4 v[106:107], off nt
	v_lshl_add_u64 v[106:107], v[104:105], 0, s[78:79]
	s_add_i32 m0, s6, 0x8000
	v_cvt_pk_bf16_f32 v174, v20, v21
	global_load_lds_dwordx4 v[106:107], off nt
	v_lshl_add_u64 v[106:107], v[104:105], 0, s[82:83]
	s_add_i32 m0, s6, 0xa000
	v_lshl_add_u64 v[104:105], v[104:105], 0, s[88:89]
	global_load_lds_dwordx4 v[106:107], off nt
	s_add_i32 m0, s6, 0xc000
	s_and_b32 s6, s8, 1
	global_load_lds_dwordx4 v[104:105], off nt
	s_mul_i32 s7, s6, 0xe000
	v_add_u32_e32 v160, s7, v101
	ds_read_b128 v[104:107], v160
	ds_read_b128 v[108:111], v160 offset:1024
	ds_read_b128 v[112:115], v160 offset:2048
	ds_read_b128 v[116:119], v160 offset:3072
	ds_read_b128 v[120:123], v160 offset:4096
	ds_read_b128 v[124:127], v160 offset:5120
	ds_read_b128 v[128:131], v160 offset:6144
	ds_read_b128 v[132:135], v160 offset:7168
	ds_read_b128 v[136:139], v160 offset:8192
	ds_read_b128 v[140:143], v160 offset:9216
	ds_read_b128 v[144:147], v160 offset:10240
	ds_read_b128 v[148:151], v160 offset:11264
	ds_read_b128 v[152:155], v160 offset:12288
	ds_read_b128 v[156:159], v160 offset:13312
	ds_read_b128 v[162:165], v160 offset:14336
	ds_read_b128 v[166:169], v160 offset:15360
	v_cvt_pk_bf16_f32 v175, v22, v23
	v_cvt_pk_bf16_f32 v176, v16, v17
	v_cvt_pk_bf16_f32 v177, v18, v19
	v_cvt_pk_bf16_f32 v178, v12, v13
	v_cvt_pk_bf16_f32 v179, v14, v15
	v_cvt_pk_bf16_f32 v180, v8, v9
	v_cvt_pk_bf16_f32 v181, v10, v11
	v_cvt_pk_bf16_f32 v196, v4, v5
	v_cvt_pk_bf16_f32 v197, v6, v7
	v_cvt_pk_bf16_f32 v198, v0, v1
	v_cvt_pk_bf16_f32 v199, v2, v3
	s_waitcnt lgkmcnt(0)
	v_mfma_f32_16x16x32_bf16 v[60:63], v[104:107], v[170:173], v[60:63]
	v_mfma_f32_16x16x32_bf16 v[56:59], v[120:123], v[170:173], v[56:59]
	v_mfma_f32_16x16x32_bf16 v[60:63], v[108:111], v[174:177], v[60:63]
	v_mfma_f32_16x16x32_bf16 v[56:59], v[124:127], v[174:177], v[56:59]
	v_mfma_f32_16x16x32_bf16 v[60:63], v[112:115], v[178:181], v[60:63]
	v_mfma_f32_16x16x32_bf16 v[56:59], v[128:131], v[178:181], v[56:59]
	v_mfma_f32_16x16x32_bf16 v[60:63], v[116:119], v[196:199], v[60:63]
	v_mfma_f32_16x16x32_bf16 v[56:59], v[132:135], v[196:199], v[56:59]
	s_waitcnt vmcnt(8)
	v_mov_b64_e32 v[32:33], v[224:225]
	v_mov_b64_e32 v[34:35], v[226:227]
	v_mov_b64_e32 v[36:37], v[228:229]
	v_mov_b64_e32 v[38:39], v[230:231]
	v_mov_b64_e32 v[40:41], v[232:233]
	v_mov_b64_e32 v[42:43], v[234:235]
	v_mov_b64_e32 v[44:45], v[236:237]
	v_mov_b64_e32 v[46:47], v[238:239]
	s_add_i32 s98, s8, 2
	s_cmp_lt_u32 s98, 4
	s_cselect_b32 s99, 3, 39
	s_sub_i32 s99, s99, s98
	s_cmp_lg_u64 s[12:13], 0
	s_cselect_b32 s98, s99, s98
	s_mov_b32 s99, 0
	s_lshl_b64 s[98:99], s[98:99], 15
	s_add_u32 s98, s23, s98
	s_addc_u32 s99, s24, s99
	v_lshl_add_u64 v[240:241], v[70:71], 2, s[98:99]
	v_lshl_add_u64 v[242:243], v[72:73], 2, s[98:99]
	v_lshl_add_u64 v[244:245], v[74:75], 2, s[98:99]
	v_lshl_add_u64 v[246:247], v[76:77], 2, s[98:99]
	global_load_dwordx4 v[236:239], v[240:241], off nt
	global_load_dwordx4 v[232:235], v[242:243], off nt
	global_load_dwordx4 v[228:231], v[244:245], off nt
	global_load_dwordx4 v[224:227], v[246:247], off nt
	ds_read_b128 v[104:107], v160 offset:16384
	ds_read_b128 v[108:111], v160 offset:17408
	ds_read_b128 v[112:115], v160 offset:18432
	ds_read_b128 v[116:119], v160 offset:19456
	ds_read_b128 v[120:123], v160 offset:20480
	ds_read_b128 v[124:127], v160 offset:21504
	ds_read_b128 v[128:131], v160 offset:22528
	ds_read_b128 v[132:135], v160 offset:23552
	v_mfma_f32_16x16x32_bf16 v[52:55], v[136:139], v[170:173], v[52:55]
	v_mfma_f32_16x16x32_bf16 v[48:51], v[152:155], v[170:173], v[48:51]
	v_mfma_f32_16x16x32_bf16 v[52:55], v[140:143], v[174:177], v[52:55]
	v_mfma_f32_16x16x32_bf16 v[48:51], v[156:159], v[174:177], v[48:51]
	v_mfma_f32_16x16x32_bf16 v[52:55], v[144:147], v[178:181], v[52:55]
	v_mfma_f32_16x16x32_bf16 v[48:51], v[162:165], v[178:181], v[48:51]
	v_mfma_f32_16x16x32_bf16 v[52:55], v[148:151], v[196:199], v[52:55]
	v_mfma_f32_16x16x32_bf16 v[48:51], v[166:169], v[196:199], v[48:51]
	ds_read_b128 v[136:139], v160 offset:24576
	ds_read_b128 v[140:143], v160 offset:25600
	ds_read_b128 v[144:147], v160 offset:26624
	ds_read_b128 v[148:151], v160 offset:27648
	ds_read_b128 v[152:155], v160 offset:28672
	ds_read_b128 v[156:159], v160 offset:29696
	ds_read_b128 v[162:165], v160 offset:30720
	ds_read_b128 v[166:169], v160 offset:31744
	s_waitcnt lgkmcnt(0)
; #define GD_LOAD8(dst, f0) do { _Pragma("unroll") for (int i_ = 0; i_ < 8; ++i_) dst[i_] = GD_FRAG((f0) + i_); } while (0)
; #define GD_PIN() __builtin_amdgcn_sched_barrier(0)
; __device__ __forceinline__ void gdn_scan_phase(const Frame& F0, const Args& a0, int nblk, bool last) {
;     ...
; #pragma unroll
;         for (int i = 0; i < 8; ++i) O[i >> 2] = __builtin_amdgcn_mfma_f32_16x16x32_bf16(fC[i], Sf[i & 3], O[i >> 2], 0, 0, 0);
;         GD_PIN(); GD_LOAD8(fB, 32); GD_PIN();
; #pragma unroll
;         for (int i = 0; i < 8; ++i) O[2 + (i >> 2)] = __builtin_amdgcn_mfma_f32_16x16x32_bf16(fA[i], Sf[i & 3], O[2 + (i >> 2)], 0, 0, 0);
;         GD_PIN(); GD_LOAD8(fC, 40); GD_PIN();
;         bf16x8 Vf[2]; Vf[0] = pack8(V[0], V[1]); Vf[1] = pack8(V[2], V[3]);
; #pragma unroll
;         for (int t = 0; t < 8; ++t) S[t] = S[t] * gl;
; #pragma unroll
;         for (int i = 0; i < 8; ++i) S[i >> 1] = __builtin_amdgcn_mfma_f32_16x16x32_bf16(fB[i], Vf[i & 1], S[i >> 1], 0, 0, 0);
;         GD_PIN();
; #pragma unroll
;         for (int i_ = 0; i_ < 8; ++i_) if (i_ != 1 && i_ != 3) fA[i_] = GD_FRAG(48 + i_);
;         GD_PIN();
; #pragma unroll
;         for (int i = 0; i < 8; ++i) S[4 + (i >> 1)] = __builtin_amdgcn_mfma_f32_16x16x32_bf16(fC[i], Vf[i & 1], S[4 + (i >> 1)], 0, 0, 0);
; #pragma unroll
;         for (int i = 0; i < 8; ++i) if (i != 1 && i != 3) O[i >> 1] = __builtin_amdgcn_mfma_f32_16x16x32_bf16(fA[i], Vf[i & 1], O[i >> 1], 0, 0, 0);
	v_mfma_f32_16x16x32_bf16 v[104:107], v[104:107], v[170:173], 0
	v_mfma_f32_16x16x32_bf16 v[104:107], v[108:111], v[174:177], v[104:107]
	v_mfma_f32_16x16x32_bf16 v[108:111], v[120:123], v[170:173], 0
	v_mfma_f32_16x16x32_bf16 v[108:111], v[124:127], v[174:177], v[108:111]
	v_mfma_f32_16x16x32_bf16 v[104:107], v[112:115], v[178:181], v[104:107]
	v_mfma_f32_16x16x32_bf16 v[108:111], v[128:131], v[178:181], v[108:111]
	v_mfma_f32_16x16x32_bf16 v[104:107], v[116:119], v[196:199], v[104:107]
	v_mfma_f32_16x16x32_bf16 v[108:111], v[132:135], v[196:199], v[108:111]
	ds_read_b128 v[112:115], v160 offset:32768
	ds_read_b128 v[116:119], v160 offset:33792
	ds_read_b128 v[120:123], v160 offset:34816
	ds_read_b128 v[124:127], v160 offset:35840
	ds_read_b128 v[128:131], v160 offset:36864
	ds_read_b128 v[132:135], v160 offset:37888
	ds_read_b128 v[200:203], v160 offset:38912
	ds_read_b128 v[204:207], v160 offset:39936
	v_mfma_f32_16x16x32_bf16 v[136:139], v[136:139], v[170:173], 0
	v_mfma_f32_16x16x32_bf16 v[136:139], v[140:143], v[174:177], v[136:139]
	v_mfma_f32_16x16x32_bf16 v[140:143], v[152:155], v[170:173], 0
	v_mfma_f32_16x16x32_bf16 v[140:143], v[156:159], v[174:177], v[140:143]
	v_mfma_f32_16x16x32_bf16 v[136:139], v[144:147], v[178:181], v[136:139]
	v_mfma_f32_16x16x32_bf16 v[140:143], v[162:165], v[178:181], v[140:143]
	v_mfma_f32_16x16x32_bf16 v[136:139], v[148:151], v[196:199], v[136:139]
	v_mfma_f32_16x16x32_bf16 v[140:143], v[166:169], v[196:199], v[140:143]
	ds_read_b128 v[144:147], v160 offset:40960
	ds_read_b128 v[148:151], v160 offset:41984
	ds_read_b128 v[152:155], v160 offset:43008
	ds_read_b128 v[156:159], v160 offset:44032
	ds_read_b128 v[162:165], v160 offset:45056
	ds_read_b128 v[166:169], v160 offset:46080
	ds_read_b128 v[170:173], v160 offset:47104
	ds_read_b128 v[174:177], v160 offset:48128
	v_cvt_pk_bf16_f32 v178, v60, v61
	v_cvt_pk_bf16_f32 v179, v62, v63
	v_cvt_pk_bf16_f32 v180, v56, v57
	v_cvt_pk_bf16_f32 v181, v58, v59
	v_pk_mul_f32 v[30:31], v[30:31], v[80:81] op_sel_hi:[1,0]
	v_pk_mul_f32 v[28:29], v[28:29], v[80:81] op_sel_hi:[1,0]
	v_pk_mul_f32 v[26:27], v[26:27], v[80:81] op_sel_hi:[1,0]
	v_pk_mul_f32 v[24:25], v[24:25], v[80:81] op_sel_hi:[1,0]
	v_pk_mul_f32 v[22:23], v[22:23], v[80:81] op_sel_hi:[1,0]
	v_pk_mul_f32 v[20:21], v[20:21], v[80:81] op_sel_hi:[1,0]
	v_pk_mul_f32 v[18:19], v[18:19], v[80:81] op_sel_hi:[1,0]
	v_pk_mul_f32 v[16:17], v[16:17], v[80:81] op_sel_hi:[1,0]
	s_waitcnt lgkmcnt(0)
	v_mfma_f32_16x16x32_bf16 v[28:31], v[112:115], v[178:181], v[28:31]
	v_cvt_pk_bf16_f32 v196, v52, v53
	v_cvt_pk_bf16_f32 v197, v54, v55
	v_cvt_pk_bf16_f32 v198, v48, v49
	v_mfma_f32_16x16x32_bf16 v[24:27], v[120:123], v[178:181], v[24:27]
	v_cvt_pk_bf16_f32 v199, v50, v51
	v_pk_mul_f32 v[14:15], v[14:15], v[80:81] op_sel_hi:[1,0]
	v_pk_mul_f32 v[12:13], v[12:13], v[80:81] op_sel_hi:[1,0]
	v_mfma_f32_16x16x32_bf16 v[20:23], v[128:131], v[178:181], v[20:23]
	v_mul_f32_e64 v10, v10, v80
	v_mul_f32_e64 v11, v11, v80
	v_pk_mul_f32 v[8:9], v[8:9], v[80:81] op_sel_hi:[1,0]
	v_pk_mul_f32 v[6:7], v[6:7], v[80:81] op_sel_hi:[1,0]
	v_mfma_f32_16x16x32_bf16 v[16:19], v[200:203], v[178:181], v[16:19]
	v_mul_f32_e64 v4, v4, v80
	v_mul_f32_e64 v5, v5, v80
	v_pk_mul_f32 v[2:3], v[2:3], v[80:81] op_sel_hi:[1,0]
	v_pk_mul_f32 v[0:1], v[0:1], v[80:81] op_sel_hi:[1,0]
	v_mfma_f32_16x16x32_bf16 v[28:31], v[116:119], v[196:199], v[28:31]
	v_mfma_f32_16x16x32_bf16 v[24:27], v[124:127], v[196:199], v[24:27]
	v_mfma_f32_16x16x32_bf16 v[20:23], v[132:135], v[196:199], v[20:23]
	v_mfma_f32_16x16x32_bf16 v[16:19], v[204:207], v[196:199], v[16:19]
	ds_read_b128 v[48:51], v160 offset:49152
	ds_read_b128 v[52:55], v160 offset:51200
	ds_read_b128 v[112:115], v160 offset:53248
	ds_read_b128 v[116:119], v160 offset:54272
	ds_read_b128 v[120:123], v160 offset:55296
	ds_read_b128 v[124:127], v160 offset:56320
	s_waitcnt lgkmcnt(0)
	v_mfma_f32_16x16x32_bf16 v[60:63], v[48:51], v[178:181], v[104:107]
	s_cmp_lt_i32 s27, 4
	s_cselect_b64 s[8:9], -1, 0
	s_and_b64 s[8:9], s[76:77], s[8:9]
	v_mfma_f32_16x16x32_bf16 v[48:51], v[112:115], v[178:181], v[136:139]
	s_and_b64 vcc, exec, s[8:9]
	v_mfma_f32_16x16x32_bf16 v[12:15], v[144:147], v[178:181], v[12:15]
	v_mfma_f32_16x16x32_bf16 v[8:11], v[152:155], v[178:181], v[8:11]
	v_mfma_f32_16x16x32_bf16 v[4:7], v[162:165], v[178:181], v[4:7]
	v_mfma_f32_16x16x32_bf16 v[0:3], v[170:173], v[178:181], v[0:3]
	v_mfma_f32_16x16x32_bf16 v[56:59], v[52:55], v[178:181], v[108:111]
	v_mfma_f32_16x16x32_bf16 v[52:55], v[116:119], v[196:199], v[48:51]
	v_mfma_f32_16x16x32_bf16 v[48:51], v[120:123], v[178:181], v[140:143]
	v_mfma_f32_16x16x32_bf16 v[12:15], v[148:151], v[196:199], v[12:15]
	v_mfma_f32_16x16x32_bf16 v[8:11], v[156:159], v[196:199], v[8:11]
	v_mfma_f32_16x16x32_bf16 v[4:7], v[166:169], v[196:199], v[4:7]
	v_mfma_f32_16x16x32_bf16 v[0:3], v[174:177], v[196:199], v[0:3]
	v_mfma_f32_16x16x32_bf16 v[48:51], v[124:127], v[196:199], v[48:51]
	s_cbranch_vccnz .LBB0_574
; #define LAS __attribute__((address_space(3)))
; #define VM_WAIT() asm volatile("s_waitcnt vmcnt(0)" ::: "memory")
; __device__ __forceinline__ unsigned pk2(float lo, float hi) { return __builtin_bit_cast(unsigned, __builtin_convertvector((f32x2p){lo, hi}, bf16x2p)); }
; #define GD_STORE_ROWS(cidx, buf) do { _Pragma("unroll") for (int i_ = 0; i_ < 2; ++i_) { const int id_ = F.tid + 512 * i_, row_ = id_ >> 4, ch_ = id_ & 15; \
;         const v4u v_ = *(const LAS v4u*)(ost + (buf) * 16384 + row_ * 256 + ((ch_ ^ (((row_ >> 2) & 3) << 2)) * 16)); \
;         *(v4u*)(GOb + (size_t)(b * TT + 64 * (cidx) + row_) * 1024 + h * 128 + ch_ * 8) = v_; } } while (0)
; __device__ __forceinline__ void gdn_scan_phase(const Frame& F0, const Args& a0, int nblk, bool last) {
;     ...
;         if (!(last && c < 4)) {
;             LAS unsigned char* ob = ost + (s & 1) * 16384;
;             const bool ev = !(cc & 1);
; #pragma unroll
;             for (int mt = 0; mt < 4; ++mt) {
;                 const float s0 = ev ? O[mt][2] : O[mt][0], s1 = ev ? O[mt][3] : O[mt][1];
;                 const float r0 = __builtin_bit_cast(float, __builtin_amdgcn_mov_dpp(__builtin_bit_cast(int, s0), 0xB1, 0xF, 0xF, true));
;                 const float r1 = __builtin_bit_cast(float, __builtin_amdgcn_mov_dpp(__builtin_bit_cast(int, s1), 0xB1, 0xF, 0xF, true));
;                 const unsigned w0 = ev ? pk2(O[mt][0], r0) : pk2(r0, O[mt][2]), w1 = ev ? pk2(O[mt][1], r1) : pk2(r1, O[mt][3]);
; #pragma unroll
;                 for (int e = 0; e < 2; ++e) { const int p = 16 * mt + 4 * g + (ev ? 0 : 2) + e, tok = d ? 63 - p : p;
;                     *(LAS unsigned*)(ob + tok * 256 + (((2 * n + (cc >> 3)) ^ (((tok >> 2) & 3) << 2)) * 16) + (cc & 6) * 2) = e ? w1 : w0; } }
;         }
;         cprev = c;
;         if (REP_SLEEP) __builtin_amdgcn_s_sleep(REP_SLEEP);
;         VM_WAIT(); __syncthreads();
;     }
;     if (!(last && cprev < 4)) GD_STORE_ROWS(cprev, 35 & 1);
	s_lshl_b32 s6, s6, 14
	s_add_i32 s6, s6, 0
	v_cmp_eq_u32_e32 vcc, 1, v68
	s_add_i32 s36, s6, 0x1c000
	v_cmp_eq_u32_e64 s[6:7], 2, v68
	v_cndmask_b32_e32 v80, v60, v61, vcc
	v_cmp_eq_u32_e64 s[8:9], 3, v68
	v_cndmask_b32_e64 v80, v80, v62, s[6:7]
	v_cmp_eq_u32_e64 s[10:11], 1, v66
	v_cndmask_b32_e64 v80, v80, v63, s[8:9]
	v_cmp_eq_u32_e64 s[14:15], 2, v66
	v_cndmask_b32_e64 v104, v60, v61, s[10:11]
	v_mov_b32_dpp v80, v80 quad_perm:[1,0,3,2] row_mask:0xf bank_mask:0xf bound_ctrl:1
	v_cndmask_b32_e64 v104, v104, v62, s[14:15]
	v_cmp_eq_u32_e64 s[16:17], 3, v66
	v_cndmask_b32_e64 v60, v80, v60, s[2:3]
	v_cndmask_b32_e64 v62, v62, v80, s[2:3]
	v_cndmask_b32_e64 v104, v104, v63, s[16:17]
	v_cvt_pk_bf16_f32 v60, v60, v62
	v_add_u32_e32 v62, s36, v97
	v_mov_b32_dpp v104, v104 quad_perm:[1,0,3,2] row_mask:0xf bank_mask:0xf bound_ctrl:1
	v_cndmask_b32_e64 v61, v104, v61, s[2:3]
	v_cndmask_b32_e64 v63, v63, v104, s[2:3]
	v_add3_u32 v62, v62, v98, v84
	ds_write_b32 v62, v60
	v_cvt_pk_bf16_f32 v60, v61, v63
	v_add_u32_e32 v61, s36, v99
	v_add3_u32 v61, v61, v100, v84
	ds_write_b32 v61, v60
	v_cndmask_b32_e32 v60, v56, v57, vcc
	v_cndmask_b32_e64 v60, v60, v58, s[6:7]
	v_cndmask_b32_e64 v60, v60, v59, s[8:9]
	v_cndmask_b32_e64 v61, v56, v57, s[10:11]
	v_cndmask_b32_e64 v61, v61, v58, s[14:15]
	v_mov_b32_dpp v60, v60 quad_perm:[1,0,3,2] row_mask:0xf bank_mask:0xf bound_ctrl:1
	v_cndmask_b32_e64 v61, v61, v59, s[16:17]
	v_cndmask_b32_e64 v56, v60, v56, s[2:3]
	v_cndmask_b32_e64 v58, v58, v60, s[2:3]
	v_mov_b32_dpp v61, v61 quad_perm:[1,0,3,2] row_mask:0xf bank_mask:0xf bound_ctrl:1
	v_cvt_pk_bf16_f32 v56, v56, v58
	v_add_u32_e32 v58, s36, v93
	v_cndmask_b32_e64 v57, v61, v57, s[2:3]
	v_cndmask_b32_e64 v59, v59, v61, s[2:3]
	v_add3_u32 v58, v58, v94, v84
	ds_write_b32 v58, v56
	v_cvt_pk_bf16_f32 v56, v57, v59
	v_add_u32_e32 v57, s36, v95
	v_add3_u32 v57, v57, v96, v84
	ds_write_b32 v57, v56
	v_cndmask_b32_e32 v56, v52, v53, vcc
	v_cndmask_b32_e64 v56, v56, v54, s[6:7]
	v_cndmask_b32_e64 v56, v56, v55, s[8:9]
	v_cndmask_b32_e64 v57, v52, v53, s[10:11]
	v_cndmask_b32_e64 v57, v57, v54, s[14:15]
	v_mov_b32_dpp v56, v56 quad_perm:[1,0,3,2] row_mask:0xf bank_mask:0xf bound_ctrl:1
	v_cndmask_b32_e64 v57, v57, v55, s[16:17]
	v_cndmask_b32_e64 v52, v56, v52, s[2:3]
	v_cndmask_b32_e64 v54, v54, v56, s[2:3]
	v_mov_b32_dpp v57, v57 quad_perm:[1,0,3,2] row_mask:0xf bank_mask:0xf bound_ctrl:1
	v_cvt_pk_bf16_f32 v52, v52, v54
	v_add_u32_e32 v54, s36, v89
	v_cndmask_b32_e64 v53, v57, v53, s[2:3]
	v_cndmask_b32_e64 v55, v55, v57, s[2:3]
	v_add3_u32 v54, v54, v90, v84
	ds_write_b32 v54, v52
	v_cvt_pk_bf16_f32 v52, v53, v55
	v_add_u32_e32 v53, s36, v91
	v_add3_u32 v53, v53, v92, v84
	ds_write_b32 v53, v52
	v_cndmask_b32_e32 v52, v48, v49, vcc
	v_cndmask_b32_e64 v52, v52, v50, s[6:7]
	v_cndmask_b32_e64 v52, v52, v51, s[8:9]
	v_cndmask_b32_e64 v53, v48, v49, s[10:11]
	v_cndmask_b32_e64 v53, v53, v50, s[14:15]
	v_mov_b32_dpp v52, v52 quad_perm:[1,0,3,2] row_mask:0xf bank_mask:0xf bound_ctrl:1
	v_cndmask_b32_e64 v53, v53, v51, s[16:17]
	v_cndmask_b32_e64 v48, v52, v48, s[2:3]
	v_cndmask_b32_e64 v50, v50, v52, s[2:3]
	v_mov_b32_dpp v53, v53 quad_perm:[1,0,3,2] row_mask:0xf bank_mask:0xf bound_ctrl:1
	v_cvt_pk_bf16_f32 v48, v48, v50
	v_add_u32_e32 v50, s36, v85
	v_cndmask_b32_e64 v49, v53, v49, s[2:3]
	v_cndmask_b32_e64 v51, v51, v53, s[2:3]
	v_add3_u32 v50, v50, v86, v84
	ds_write_b32 v50, v48
	v_cvt_pk_bf16_f32 v48, v49, v51
	v_add_u32_e32 v49, s36, v87
	v_add3_u32 v49, v49, v88, v84
	ds_write_b32 v49, v48
.LBB0_574:
	s_waitcnt vmcnt(4)
	s_add_i32 s26, s26, -1
	s_addk_i32 s19, 0x4000
	s_cmp_eq_u32 s26, 3
	s_waitcnt vmcnt(4) lgkmcnt(0)
	s_barrier
	s_cbranch_scc0 .LBB0_567
	s_cmp_lt_i32 s27, s22
	s_cbranch_scc1 .LBB0_577
	s_lshl_b32 s0, s27, 6
	v_add_u32_e32 v48, v102, v83
	s_add_i32 s0, s0, s18
	ds_read_b128 v[48:51], v48
	v_add_u32_e32 v52, s0, v82
	v_ashrrev_i32_e32 v53, 31, v52
	v_lshlrev_b64 v[52:53], 11, v[52:53]
	v_lshl_add_u64 v[52:53], v[64:65], 0, v[52:53]
	s_waitcnt lgkmcnt(0)
	global_store_dwordx4 v[52:53], v[48:51], off nt
	v_add_u32_e32 v52, s0, v69
	v_ashrrev_i32_e32 v53, 31, v52
	v_add_u32_e32 v48, v102, v81
	ds_read_b128 v[48:51], v48
	v_lshlrev_b64 v[52:53], 11, v[52:53]
	v_lshl_add_u64 v[52:53], v[64:65], 0, v[52:53]
	s_waitcnt lgkmcnt(0)
	global_store_dwordx4 v[52:53], v[48:51], off nt
